# in-proj A: two CU groups, second starts each chunk 4 us late (de-phase epilogue store bursts)
# baseline (speedup 1.0000x reference)
; #define PG8_LAS __attribute__((address_space(3)))
;     __device__ __forceinline__ void stage_consts(PG8_LAS float* gl, int tid) const { if (tid < 2 * NGQ) gl[tid] = (tid < NGQ) ? qg[tid] * qscale : kg[tid - NGQ]; }
; #define PG8_STAGE(bufoff, gbase, voff) do { _Pragma("unroll") for (int _i = 0; _i < 2; ++_i) \
;         __builtin_amdgcn_global_load_lds((const unsigned*)((const char*)(gbase) + (voff)[_i]), (PG8_LAS unsigned*)(lds + (bufoff) + ldsw + _i * 8192), 16, 0, 0); } while (0)
; #define PG8_ZERO4(x) do { unsigned long long z0_, z1_; asm volatile("v_mov_b64 %0, 0\n\tv_mov_b64 %1, 0" : "=v"(z0_), "=v"(z1_)); typedef unsigned long long u64x2_ __attribute__((ext_vector_type(2))); (x) = __builtin_bit_cast(f32x4, (u64x2_){z0_, z1_}); } while (0)
;     ...
;     Unit cur, nxt; int ui = 0; int prev_pm = -1;
;     if (!S.next(0, cur)) return;
;     f32x4 acc[2][2][4][2];
; #pragma unroll
;     for (int a = 0; a < 2; ++a)
; #pragma unroll
;         for (int b = 0; b < 2; ++b)
; #pragma unroll
;             for (int m = 0; m < 4; ++m)
; #pragma unroll
;                 for (int n = 0; n < 2; ++n) PG8_ZERO4(acc[a][b][m][n]);
;     bf16x8 At[4][2], B0[2][2], B1[2][2];
;     const char* cA = (const char*)g.A + (size_t)cur.pm * tstep; const char* cB = (const char*)g.Bt + (size_t)cur.pn * tstep;
;     PG8_STAGE(PG8_SB(0, 0), cB, voffB); PG8_STAGE(PG8_SB(0, 1), cB + hstepB, voffB); PG8_STAGE(PG8_SA(0, 0), cA, voffA); PG8_STAGE(PG8_SA(0, 1), cA + hstep, voffA);
;     E.stage_consts((PG8_LAS float*)(lds + 131072) + 1024, tid);
; __global__ void __launch_bounds__(NWAVES * 64, 2) fwd_kernel(Args args) {
;     ...
;             if (STAG_IN > 0) { const unsigned long long t0_ = __builtin_amdgcn_s_memrealtime(), dl_ = (unsigned long long)((F.vcu % 5) * STAG_IN);
;                 while (__builtin_amdgcn_s_memrealtime() - t0_ < dl_) __builtin_amdgcn_s_sleep(4); }
;             pg8::Gemm g{XB + (size_t)hf * MCH * DM, (const bf16*)(ws + WS_WAIN), MCH, NA_IN, DM};
.LBB0_190:
	s_lshl_b32 s62, s85, 1
	s_or_b32 s2, s62, 1
	s_cmp_le_i32 s66, s2
	s_cselect_b64 s[12:13], -1, 0
	s_cmp_lt_i32 s2, s67
	s_cselect_b64 s[14:15], -1, 0
	s_lshl_b32 s88, s85, 23
	s_and_b64 s[12:13], s[12:13], s[14:15]
	s_lshl_b64 s[14:15], s[88:89], 1
	s_add_u32 s16, s63, s14
	s_addc_u32 s17, s64, s15
	s_cmp_eq_u32 s85, 3
	s_cselect_b64 s[22:23], -1, 0
	s_cmp_lg_u32 s85, 3
	s_cselect_b64 s[14:15], -1, 0
	v_writelane_b32 v252, s14, 43
	s_add_i32 s2, s62, 2
	s_nop 0
	v_writelane_b32 v252, s15, 44
	s_lshl_b32 s14, s85, 6
	s_mov_b32 s15, s89
	v_writelane_b32 v252, s14, 45
	s_cmp_le_i32 s66, s2
	s_nop 0
	v_writelane_b32 v252, s15, 46
	s_cselect_b64 s[14:15], -1, 0
	s_cmp_lt_i32 s2, s67
	s_cselect_b64 s[18:19], -1, 0
	s_and_b64 s[18:19], s[14:15], s[18:19]
	s_and_b64 vcc, exec, s[12:13]
	s_cbranch_vccz .LBB0_302
	s_lshr_b32 s100, s87, 3
	s_and_b32 s100, s100, 1
	s_mul_i32 s100, s100, 4
.Lstag_a_loop:
	s_cmp_eq_u32 s100, 0
	s_cbranch_scc1 .Lstag_a_done
	s_sleep 32
	s_sub_u32 s100, s100, 1
	s_branch .Lstag_a_loop
.Lstag_a_done:
	v_readlane_b32 s12, v253, 57
	s_waitcnt vmcnt(0)
	v_mbcnt_lo_u32_b32 v8, -1, 0
	v_mbcnt_hi_u32_b32 v8, -1, v8
	v_readlane_b32 s13, v253, 58
	v_add_u32_e32 v0, s65, v8
	s_andn2_b64 vcc, exec, s[12:13]
	v_readfirstlane_b32 s2, v0
	s_cbranch_vccnz .LBB0_254
	v_lshlrev_b32_e32 v1, 4, v0
	v_add_u32_e32 v2, 0x2000, v1
	v_ashrrev_i32_e32 v3, 31, v2
	v_lshrrev_b32_e32 v3, 22, v3
	v_add_u32_e32 v3, v2, v3
	v_ashrrev_i32_e32 v9, 10, v3
	v_mul_i32_i24_e32 v3, 0x400, v9
	v_sub_u32_e32 v2, v2, v3
	v_lshrrev_b32_e32 v3, 4, v2
	v_bitop3_b32 v2, v3, v2, 32 bitop3:0x6c
	v_ashrrev_i32_e32 v3, 31, v2
	v_lshrrev_b32_e32 v3, 26, v3
	v_add_u32_e32 v3, v2, v3
	v_lshlrev_b32_e32 v5, 3, v9
	v_ashrrev_i32_e32 v10, 6, v3
	v_and_b32_e32 v5, -16, v5
	v_add_u32_e32 v5, v10, v5
	v_lshrrev_b32_e32 v6, 2, v5
	v_lshlrev_b32_e32 v7, 1, v5
	v_and_b32_e32 v3, 0xc0, v3
	v_and_b32_e32 v4, 3, v10
	v_and_b32_e32 v6, 4, v6
	v_and_b32_e32 v7, 0x1fffd8, v7
	v_sub_u32_e32 v2, v2, v3
	v_or3_b32 v4, v4, v6, v7
	v_lshlrev_b32_e32 v6, 5, v9
	v_ashrrev_i16_sdwa v2, v191, sext(v2) dst_sel:DWORD dst_unused:UNUSED_PAD src0_sel:DWORD src1_sel:BYTE_0
	v_and_b32_e32 v6, 32, v6
	v_bfe_i32 v11, v2, 0, 16
	v_add_lshl_u32 v2, v6, v11, 1
	v_lshl_add_u32 v166, v4, 11, v2
	v_lshl_add_u32 v168, v5, 11, v2
	v_bfe_i32 v2, v0, 27, 1
	v_lshrrev_b32_e32 v2, 22, v2
	v_add_u32_e32 v2, v1, v2
	v_and_b32_e32 v2, 0xfffffc00, v2
	v_sub_u32_e32 v1, v1, v2
	v_lshrrev_b32_e32 v2, 4, v1
	v_bitop3_b32 v2, v2, v1, 32 bitop3:0x6c
	v_ashrrev_i32_e32 v1, 31, v2
	v_lshrrev_b32_e32 v1, 26, v1
	v_add_u32_e32 v3, v2, v1
	v_ashrrev_i32_e32 v1, 31, v0
	v_lshrrev_b32_e32 v5, 26, v1
	v_add_u32_e32 v5, v0, v5
	v_ashrrev_i32_e32 v13, 6, v5
	v_lshlrev_b32_e32 v5, 3, v13
	v_ashrrev_i32_e32 v12, 6, v3
	v_and_b32_e32 v5, -16, v5
	v_add_u32_e32 v5, v12, v5
	v_lshrrev_b32_e32 v6, 2, v5
	v_lshlrev_b32_e32 v7, 1, v5
	v_and_b32_e32 v3, 0xc0, v3
	v_and_b32_e32 v4, 3, v12
	v_and_b32_e32 v6, 4, v6
	v_and_b32_e32 v7, 0x1fffd8, v7
	v_sub_u32_e32 v2, v2, v3
	s_ashr_i32 s14, s2, 6
	v_or3_b32 v4, v4, v6, v7
	v_lshlrev_b32_e32 v6, 5, v13
	v_ashrrev_i16_sdwa v2, v191, sext(v2) dst_sel:DWORD dst_unused:UNUSED_PAD src0_sel:DWORD src1_sel:BYTE_0
	s_lshl_b32 s15, s14, 10
	v_and_b32_e32 v6, 32, v6
	v_bfe_i32 v14, v2, 0, 16
	v_add_lshl_u32 v2, v6, v14, 1
	s_add_i32 s63, s15, 0
	v_readlane_b32 s12, v252, 13
	v_lshl_add_u32 v170, v4, 11, v2
	s_add_i32 m0, s63, 0x10000
	v_readlane_b32 s13, v252, 14
	v_mov_b64 v[132:133], 0
	v_mov_b64 v[134:135], 0
	v_mov_b64 v[128:129], 0
	v_mov_b64 v[130:131], 0
	v_mov_b64 v[116:117], 0
	v_mov_b64 v[118:119], 0
	v_mov_b64 v[112:113], 0
	v_mov_b64 v[114:115], 0
	v_mov_b64 v[100:101], 0
	v_mov_b64 v[102:103], 0
	v_mov_b64 v[96:97], 0
	v_mov_b64 v[98:99], 0
	v_mov_b64 v[84:85], 0
	v_mov_b64 v[86:87], 0
	v_mov_b64 v[80:81], 0
	v_mov_b64 v[82:83], 0
	v_mov_b64 v[140:141], 0
	v_mov_b64 v[142:143], 0
	v_mov_b64 v[136:137], 0
	v_mov_b64 v[138:139], 0
	v_mov_b64 v[124:125], 0
	v_mov_b64 v[126:127], 0
	v_mov_b64 v[120:121], 0
	v_mov_b64 v[122:123], 0
	v_mov_b64 v[108:109], 0
	v_mov_b64 v[110:111], 0
	v_mov_b64 v[104:105], 0
	v_mov_b64 v[106:107], 0
	v_mov_b64 v[92:93], 0
	v_mov_b64 v[94:95], 0
	v_mov_b64 v[88:89], 0
	v_mov_b64 v[90:91], 0
	v_mov_b64 v[68:69], 0
	v_mov_b64 v[70:71], 0
	v_mov_b64 v[64:65], 0
	v_mov_b64 v[66:67], 0
	v_mov_b64 v[52:53], 0
	v_mov_b64 v[54:55], 0
	v_mov_b64 v[48:49], 0
	v_mov_b64 v[50:51], 0
	v_mov_b64 v[36:37], 0
	v_mov_b64 v[38:39], 0
	v_mov_b64 v[32:33], 0
	v_mov_b64 v[34:35], 0
	v_mov_b64 v[20:21], 0
	v_mov_b64 v[22:23], 0
	v_mov_b64 v[16:17], 0
	v_mov_b64 v[18:19], 0
	v_mov_b64 v[76:77], 0
	v_mov_b64 v[78:79], 0
	v_mov_b64 v[72:73], 0
	v_mov_b64 v[74:75], 0
	v_mov_b64 v[60:61], 0
	v_mov_b64 v[62:63], 0
	v_mov_b64 v[56:57], 0
	v_mov_b64 v[58:59], 0
	v_mov_b64 v[44:45], 0
	v_mov_b64 v[46:47], 0
	v_mov_b64 v[40:41], 0
	v_mov_b64 v[42:43], 0
	v_mov_b64 v[24:25], 0
	v_mov_b64 v[26:27], 0
	v_mov_b64 v[28:29], 0
	v_mov_b64 v[30:31], 0
	s_nop 4
	global_load_lds_dwordx4 v170, s[12:13]
	s_add_i32 m0, s63, 0x12000
	v_lshl_add_u32 v172, v5, 11, v2
	global_load_lds_dwordx4 v166, s[12:13]
	v_readlane_b32 s12, v252, 11
	s_add_i32 m0, s63, 0x14000
	v_readlane_b32 s13, v252, 12
	s_nop 4
	global_load_lds_dwordx4 v170, s[12:13]
	s_add_i32 m0, s63, 0x16000
	s_nop 0
	global_load_lds_dwordx4 v166, s[12:13]
	v_readlane_b32 s12, v252, 9
	v_readlane_b32 s13, v252, 10
	s_add_u32 s38, s16, s12
	s_addc_u32 s39, s17, s13
	s_add_i32 s64, s63, 0x2000
	s_mov_b32 m0, s63
	s_add_u32 s12, s38, 0x40000
	global_load_lds_dwordx4 v172, s[38:39]
	s_mov_b32 m0, s64
	s_addc_u32 s13, s39, 0
	s_add_i32 s65, s63, 0x4000
	global_load_lds_dwordx4 v168, s[38:39]
	s_mov_b32 m0, s65
	s_add_i32 s66, s63, 0x6000
	global_load_lds_dwordx4 v172, s[12:13]
	s_mov_b32 m0, s66
	s_nop 0
	global_load_lds_dwordx4 v168, s[12:13]
	s_movk_i32 s12, 0x180
	v_cmp_gt_i32_e32 vcc, s12, v0
	s_and_saveexec_b64 s[20:21], vcc
	s_cbranch_execz .LBB0_198
	s_movk_i32 s12, 0xbf
	v_cmp_lt_i32_e32 vcc, s12, v0
	s_and_saveexec_b64 s[12:13], vcc
	s_xor_b64 s[24:25], exec, s[12:13]
	s_cbranch_execz .LBB0_195
	v_mov_b32_e32 v1, v161
	v_lshl_add_u64 v[2:3], v[0:1], 2, s[54:55]
	global_load_dword v2, v[2:3], off offset:-768
